# v24 + static s_setprio 1 moved to waves 0-3 (instead of 4-7) in B/C/D attention units
# speedup vs baseline: 1.0018x; 1.0018x over previous
; #define LAS __attribute__((address_space(3)))
; #define GASA __attribute__((address_space(1)))
; template <int DQK, int DV, bool BAND>
; DI void attn_unit(const AttnArgs& a, LAS unsigned char* lds, int tid) {
;     ...
;     const int lane = tid & 63, wid = __builtin_amdgcn_readfirstlane(tid >> 6), r32 = lane & 31, hi = lane >> 5;
;     LAS float* scr = (LAS float*)(lds + SCR + wid * 256);
;     const unsigned lds0 = (unsigned)(uintptr_t)lds;
;     bf16x8 qf[ND0];
;     { const GASA bf16_t* qrow = (const GASA bf16_t*)a.q + (long)(wid * 32 + r32) * a.qs;
; #pragma unroll
;       for (int d0 = 0; d0 < ND0; ++d0) qf[d0] = *(const GASA bf16x8*)(qrow + d0 * 16 + hi * 8); }
; #pragma unroll
;     for (int d0 = 0; d0 < ND0; ++d0) asm volatile("" : "+v"(qf[d0]));
;     asm volatile("s_waitcnt vmcnt(0)" ::: "memory");
;     int t_lo = 0, t_hi = a.kv_len >> 6;
;     if (BAND) { const int tb = (a.q0 >> 6) - 1; t_lo = tb < 0 ? 0 : tb; const int te = (a.q0 >> 6) + 5; t_hi = te < t_hi ? te : t_hi; }
;     const int qw = a.q0 + wid * 32;
;     ...
;     if (wid >= 4) __builtin_amdgcn_s_setprio(1);
; __global__ void __launch_bounds__(512, 2) mega_fwd(Params p) {
;     ...
;                         for (int u = vcu; u < nunits; u += G) {
;                             int r = u; const int qb = r % nqb; r /= nqb; const int h = r % 16; const int sq = r / 16;
;                             const size_t row0 = (size_t)sq * S;
;                             AttnArgs a; a.nomax = 0; a.q = QD + (row0 + qb * 256) * 1536 + h * 96; a.qs = 1536; a.k = KVD + row0 * 2048 + h * 128; a.ks = 2048; a.k2 = KR + row0 * 32; a.k2s = 32;
;                             a.v = KVD + row0 * 2048 + h * 128 + 64; a.vs = 2048; a.o = AO + (row0 + qb * 256) * 1024 + h * 64; a.os = 1024; a.lse = nullptr; a.lses = 0;
;                             a.kv_len = S; a.q0 = qb * 256;
;                             attn_unit<96, 64, false>(a, lds, tid);
.LBB0_168:
	s_ashr_i32 s24, s26, 31
	v_readlane_b32 s27, v254, 31
	s_xor_b32 s24, s24, s27
	s_abs_i32 s27, s26
	v_readlane_b32 s34, v254, 33
	s_mul_hi_u32 s34, s27, s34
	v_readlane_b32 s41, v254, 32
	s_mul_i32 s35, s34, s41
	s_sub_i32 s27, s27, s35
	s_add_i32 s35, s34, 1
	s_sub_i32 s40, s27, s41
	s_cmp_ge_u32 s27, s41
	s_cselect_b32 s34, s35, s34
	s_cselect_b32 s27, s40, s27
	s_add_i32 s35, s34, 1
	s_cmp_ge_u32 s27, s41
	s_cselect_b32 s27, s35, s34
	s_xor_b32 s27, s27, s24
	s_sub_i32 s24, s27, s24
	s_ashr_i32 s34, s24, 31
	s_lshr_b32 s34, s34, 28
	v_readlane_b32 s27, v254, 30
	s_add_i32 s34, s24, s34
	s_mul_i32 s27, s24, s27
	s_ashr_i32 s40, s34, 4
	s_and_b32 s34, s34, -16
	s_sub_i32 s27, s26, s27
	s_sub_i32 s34, s24, s34
	s_ashr_i32 s41, s40, 31
	v_readlane_b32 s24, v254, 22
	s_lshl_b64 s[40:41], s[40:41], s24
	s_lshl_b32 s24, s27, 8
	s_ashr_i32 s27, s24, 31
	s_add_u32 s42, s40, s24
	s_addc_u32 s43, s41, s27
	s_mul_i32 s24, s43, 0xc00
	s_mul_hi_u32 s27, s42, 0xc00
	s_add_i32 s27, s27, s24
	s_mul_i32 s24, s42, 0xc00
	s_add_u32 s24, s16, s24
	s_mul_i32 s44, s34, 0x60
	s_addc_u32 s27, s17, s27
	s_ashr_i32 s45, s44, 31
	s_lshl_b64 s[44:45], s[44:45], 1
	s_add_u32 s44, s24, s44
	v_readfirstlane_b32 s52, v177
	s_addc_u32 s45, s27, s45
	s_ashr_i32 s35, s52, 6
	s_lshl_b32 s27, s35, 5
	v_or_b32_e32 v2, s27, v157
	v_mov_b64_e32 v[0:1], s[44:45]
	v_mad_i64_i32 v[0:1], s[44:45], v2, s95, v[0:1]
	v_mov_b32_e32 v171, v195
	v_lshl_add_u64 v[0:1], v[0:1], 0, v[170:171]
	global_load_dwordx4 v[96:99], v[0:1], off
	global_load_dwordx4 v[100:103], v[0:1], off offset:32
	global_load_dwordx4 v[104:107], v[0:1], off offset:64
	global_load_dwordx4 v[108:111], v[0:1], off offset:96
	global_load_dwordx4 v[112:115], v[0:1], off offset:128
	global_load_dwordx4 v[116:119], v[0:1], off offset:160
	s_cmp_lt_i32 s35, 4
	s_nop 0
	s_nop 0
	s_nop 0
	s_nop 0
	s_nop 0
	s_nop 0
	s_nop 0
	s_cbranch_scc0 .LBB0_170
	s_setprio 1

; #define LAS __attribute__((address_space(3)))
; #define GASA __attribute__((address_space(1)))
; template <int DQK, int DV, bool BAND>
; DI void attn_unit(const AttnArgs& a, LAS unsigned char* lds, int tid) {
;     ...
;     const int lane = tid & 63, wid = __builtin_amdgcn_readfirstlane(tid >> 6), r32 = lane & 31, hi = lane >> 5;
;     LAS float* scr = (LAS float*)(lds + SCR + wid * 256);
;     const unsigned lds0 = (unsigned)(uintptr_t)lds;
;     bf16x8 qf[ND0];
;     { const GASA bf16_t* qrow = (const GASA bf16_t*)a.q + (long)(wid * 32 + r32) * a.qs;
; #pragma unroll
;       for (int d0 = 0; d0 < ND0; ++d0) qf[d0] = *(const GASA bf16x8*)(qrow + d0 * 16 + hi * 8); }
; #pragma unroll
;     for (int d0 = 0; d0 < ND0; ++d0) asm volatile("" : "+v"(qf[d0]));
;     asm volatile("s_waitcnt vmcnt(0)" ::: "memory");
;     int t_lo = 0, t_hi = a.kv_len >> 6;
;     if (BAND) { const int tb = (a.q0 >> 6) - 1; t_lo = tb < 0 ? 0 : tb; const int te = (a.q0 >> 6) + 5; t_hi = te < t_hi ? te : t_hi; }
;     const int qw = a.q0 + wid * 32;
;     ...
;     if (wid >= 4) __builtin_amdgcn_s_setprio(1);
; __global__ void __launch_bounds__(512, 2) mega_fwd(Params p) {
;     ...
;                         for (int u = vcu; u < nunits; u += G) {
;                             int r = u; const int qb = r % nqb; r /= nqb; const int hc = r % 16; const int sq = r / 16;
;                             const size_t row0 = (size_t)sq * S;
;                             AttnArgs a; a.nomax = 0; a.q = BIG + (row0 + qb * 256) * 3072 + hc * 64; a.qs = 3072; a.k = BIG + row0 * 3072 + 1024 + hc * 64; a.ks = 3072; a.k2 = nullptr; a.k2s = 0;
;                             a.v = BIG + row0 * 3072 + 2048 + (hc >> 1) * 128; a.vs = 3072; a.o = OC + (row0 + qb * 256) * 2048 + hc * 128; a.os = 2048; a.lse = nullptr; a.lses = 0;
;                             a.kv_len = S; a.q0 = qb * 256;
;                             attn_unit<64, 128, false>(a, lds, tid);
.LBB0_208:
	s_ashr_i32 s17, s16, 31
	v_readlane_b32 s18, v254, 31
	s_xor_b32 s17, s17, s18
	s_abs_i32 s18, s16
	v_readlane_b32 s19, v254, 33
	s_mul_hi_u32 s19, s18, s19
	v_readlane_b32 s27, v254, 32
	s_mul_i32 s24, s19, s27
	s_sub_i32 s18, s18, s24
	s_add_i32 s24, s19, 1
	s_sub_i32 s26, s18, s27
	s_cmp_ge_u32 s18, s27
	s_cselect_b32 s19, s24, s19
	s_cselect_b32 s18, s26, s18
	s_add_i32 s24, s19, 1
	s_cmp_ge_u32 s18, s27
	s_cselect_b32 s18, s24, s19
	s_xor_b32 s18, s18, s17
	s_sub_i32 s17, s18, s17
	v_readlane_b32 s18, v254, 30
	s_mul_i32 s18, s17, s18
	s_sub_i32 s19, s16, s18
	s_ashr_i32 s18, s17, 31
	s_lshr_b32 s18, s18, 28
	s_add_i32 s18, s17, s18
	s_ashr_i32 s26, s18, 4
	s_and_b32 s18, s18, -16
	s_sub_i32 s18, s17, s18
	s_ashr_i32 s27, s26, 31
	v_readlane_b32 s17, v254, 22
	s_lshl_b64 s[46:47], s[26:27], s17
	s_lshl_b32 s17, s19, 8
	s_ashr_i32 s19, s17, 31
	s_add_u32 s42, s46, s17
	s_addc_u32 s43, s47, s19
	s_mul_i32 s17, s43, 0x1800
	s_mul_hi_u32 s19, s42, 0x1800
	s_add_i32 s19, s19, s17
	s_mul_i32 s17, s42, 0x1800
	s_add_u32 s17, s70, s17
	s_addc_u32 s19, s71, s19
	s_lshl_b32 s48, s18, 6
	s_ashr_i32 s49, s48, 31
	s_lshl_b64 s[40:41], s[48:49], 1
	s_add_u32 s26, s17, s40
	v_readfirstlane_b32 s17, v177
	s_addc_u32 s27, s19, s41
	s_ashr_i32 s19, s17, 6
	s_lshl_b32 s17, s19, 5
	v_or_b32_e32 v2, s17, v196
	v_mov_b64_e32 v[0:1], s[26:27]
	s_movk_i32 s24, 0x1800
	v_mad_i64_i32 v[0:1], s[26:27], v2, s24, v[0:1]
	v_lshl_add_u64 v[0:1], v[0:1], 0, v[194:195]
	global_load_dwordx4 v[128:131], v[0:1], off
	global_load_dwordx4 v[132:135], v[0:1], off offset:32
	global_load_dwordx4 v[136:139], v[0:1], off offset:64
	global_load_dwordx4 v[140:143], v[0:1], off offset:96
	s_cmp_lt_i32 s19, 4
	s_nop 0
	s_nop 0
	s_nop 0
	s_nop 0
	s_nop 0
	s_cbranch_scc0 .LBB0_210
	s_setprio 1

; #define LAS __attribute__((address_space(3)))
; #define GASA __attribute__((address_space(1)))
; template <int DQK, int DV, bool BAND>
; DI void attn_unit(const AttnArgs& a, LAS unsigned char* lds, int tid) {
;     ...
;     const int lane = tid & 63, wid = __builtin_amdgcn_readfirstlane(tid >> 6), r32 = lane & 31, hi = lane >> 5;
;     LAS float* scr = (LAS float*)(lds + SCR + wid * 256);
;     const unsigned lds0 = (unsigned)(uintptr_t)lds;
;     bf16x8 qf[ND0];
;     { const GASA bf16_t* qrow = (const GASA bf16_t*)a.q + (long)(wid * 32 + r32) * a.qs;
; #pragma unroll
;       for (int d0 = 0; d0 < ND0; ++d0) qf[d0] = *(const GASA bf16x8*)(qrow + d0 * 16 + hi * 8); }
; #pragma unroll
;     for (int d0 = 0; d0 < ND0; ++d0) asm volatile("" : "+v"(qf[d0]));
;     asm volatile("s_waitcnt vmcnt(0)" ::: "memory");
;     int t_lo = 0, t_hi = a.kv_len >> 6;
;     if (BAND) { const int tb = (a.q0 >> 6) - 1; t_lo = tb < 0 ? 0 : tb; const int te = (a.q0 >> 6) + 5; t_hi = te < t_hi ? te : t_hi; }
;     const int qw = a.q0 + wid * 32;
;     ...
;     if (wid >= 4) __builtin_amdgcn_s_setprio(1);
; __global__ void __launch_bounds__(512, 2) mega_fwd(Params p) {
;     ...
;                         for (int u = vcu; u < nunits; u += G) {
;                             int r = u; const int qb = r % nqb; r /= nqb; const int h = r % 16; const int sq = r / 16;
;                             const size_t row0 = (size_t)sq * S;
;                             AttnArgs a; a.nomax = 0; a.q = BIG + (row0 + qb * 256) * 1536 + h * 64; a.qs = 1536; a.k = BIG + row0 * 1536 + 1024 + (h >> 2) * 64; a.ks = 1536; a.k2 = nullptr; a.k2s = 0;
;                             a.v = BIG + row0 * 1536 + 1280 + (h >> 2) * 64; a.vs = 1536; a.o = AO + (row0 + qb * 256) * 1024 + h * 64; a.os = 1024; a.lse = nullptr; a.lses = 0;
;                             a.kv_len = S; a.q0 = qb * 256; a.nomax = lamp[1] <= 40.0f ? 1 : 0;
;                             attn_unit<64, 64, false>(a, lds, tid);
.LBB0_235:
	s_ashr_i32 s13, s12, 31
	v_readlane_b32 s16, v254, 31
	s_xor_b32 s13, s13, s16
	s_abs_i32 s16, s12
	v_readlane_b32 s17, v254, 33
	s_mul_hi_u32 s17, s16, s17
	v_readlane_b32 s24, v254, 32
	s_mul_i32 s18, s17, s24
	s_sub_i32 s16, s16, s18
	s_add_i32 s18, s17, 1
	s_sub_i32 s19, s16, s24
	s_cmp_ge_u32 s16, s24
	s_cselect_b32 s17, s18, s17
	s_cselect_b32 s16, s19, s16
	s_add_i32 s18, s17, 1
	s_cmp_ge_u32 s16, s24
	s_cselect_b32 s16, s18, s17
	s_xor_b32 s16, s16, s13
	s_sub_i32 s13, s16, s13
	s_ashr_i32 s17, s13, 31
	s_lshr_b32 s17, s17, 28
	v_readlane_b32 s16, v254, 30
	s_add_i32 s17, s13, s17
	s_mul_i32 s16, s13, s16
	s_ashr_i32 s18, s17, 4
	s_and_b32 s17, s17, -16
	s_sub_i32 s16, s12, s16
	s_sub_i32 s17, s13, s17
	s_ashr_i32 s19, s18, 31
	v_readlane_b32 s13, v254, 22
	s_lshl_b64 s[40:41], s[18:19], s13
	s_lshl_b32 s13, s16, 8
	s_ashr_i32 s16, s13, 31
	s_add_u32 s42, s40, s13
	s_addc_u32 s43, s41, s16
	s_mul_i32 s13, s43, 0xc00
	s_mul_hi_u32 s16, s42, 0xc00
	s_add_i32 s16, s16, s13
	s_mul_i32 s13, s42, 0xc00
	s_add_u32 s13, s70, s13
	s_addc_u32 s16, s71, s16
	s_lshl_b32 s18, s17, 6
	s_ashr_i32 s19, s18, 31
	s_lshl_b64 s[46:47], s[18:19], 1
	s_add_u32 s26, s13, s46
	v_readfirstlane_b32 s18, v177
	s_addc_u32 s27, s16, s47
	s_ashr_i32 s16, s18, 6
	s_lshl_b32 s13, s16, 5
	v_or_b32_e32 v2, s13, v160
	v_mov_b64_e32 v[0:1], s[26:27]
	v_mad_i64_i32 v[0:1], s[26:27], v2, s95, v[0:1]
	v_lshl_add_u64 v[0:1], v[0:1], 0, v[194:195]
	global_load_dwordx4 v[96:99], v[0:1], off
	global_load_dwordx4 v[100:103], v[0:1], off offset:32
	global_load_dwordx4 v[104:107], v[0:1], off offset:64
	global_load_dwordx4 v[108:111], v[0:1], off offset:96
	v_readlane_b32 s26, v254, 61
	v_readlane_b32 s27, v254, 62
	s_cmp_lt_i32 s16, 4
	s_nop 0
	v_mov_b64_e32 v[0:1], s[26:27]
	flat_load_dword v0, v[0:1] offset:4
	s_waitcnt vmcnt(0)
	s_waitcnt vmcnt(0)
	s_cbranch_scc0 .LBB0_237
	s_setprio 1
